# adaLN layers 1-3 on scan-idle CUs + prologue: layer-0 adaLN on CUs 0-63 while CUs 64-255 convert 21K items; scan0 29K / scan2 38K items
# baseline (speedup 1.0000x reference)
; #define LAS __attribute__((address_space(3)))
; DI void phase_prologue(const Frame& F0, const Args& a) {
;     ...
;         LAS float* scr = (LAS float*)(F.lds + 43008 + F.wave * 8448);
;         const int gw = F.vcu * NWAVES + F.wave, NGW = F.G * NWAVES;
;         constexpr int I_IN = 32 * (GIN / 32), I_SQ = 32 * 64, I_GU = 32 * (2 * DFF / 32), I_DN = (DFF / 64) * 64;
;         constexpr int NITEMS = 2 * I_IN + 2 * I_SQ + 2 * I_SQ + DEPTH * I_GU + DEPTH * I_DN;
;         for (int it = gw; it < NITEMS; it += NGW) {
.LBB0_79:
	s_or_b64 exec, exec, s[8:9]
	s_lshl_b32 s0, s60, 3
	s_add_i32 s6, s0, s44
	s_cmp_gt_i32 s6, 0x1583f
	s_cbranch_scc1 .LBB0_11
	s_mov_b32 s90, s6
	s_mov_b32 s92, 0
	s_mov_b32 s91, 0x15840
	v_readlane_b32 s93, v252, 53
	s_cmp_eq_u32 s3, 0x100
	s_cbranch_scc0 .Lconv_entry
	s_mov_b32 s92, 1
	s_mov_b32 s91, 0x52b8
	s_cmp_lt_u32 s60, 64
	s_cbranch_scc1 .Lconv_exit
	s_sub_u32 s90, s90, 0x200
	s_movk_i32 s93, 0x600

; DI void phase_prologue(const Frame& F0, const Args& a) {
;     ...
;         for (int it = gw; it < NITEMS; it += NGW) {
;             int r = it;
;             if (r < 2 * I_IN) { const int j = r / I_IN; r %= I_IN; const int nblk = GIN / 32, kb = r / nblk, nb = r % nblk;
;                 transpose_item(a.gla_w_in + (size_t)j * DM * GIN, DM, GIN, (bf16*)(ws + WS_WIN) + (size_t)j * GIN_PAD * DM, 64 * kb, 32 * nb, 32 * nb, scr, F.lane); continue; }
;             r -= 2 * I_IN;
;             if (r < 2 * I_SQ) { const int j = r / I_SQ; r %= I_SQ; const int kb = r / 64, nb = r % 64;
;                 transpose_item(a.gla_w_out + (size_t)j * DM * DM, DM, DM, (bf16*)(ws + WS_WGO) + (size_t)j * DM * DM, 64 * kb, 32 * nb, 32 * nb, scr, F.lane); continue; }
;             r -= 2 * I_SQ;
;             if (r < 2 * I_SQ) { const int j = r / I_SQ; r %= I_SQ; const int kb = r / 64, nb = r % 64;
;                 transpose_item(a.fnet_w_out + (size_t)j * DM * DM, DM, DM, (bf16*)(ws + WS_WFO) + (size_t)j * DM * DM, 64 * kb, 32 * nb, 32 * nb, scr, F.lane, 1); continue; }
;             r -= 2 * I_SQ;
;             if (r < DEPTH * I_GU) { const int j = r / I_GU; r %= I_GU; const int nblk = 2 * DFF / 32, kb = r / nblk, nb = r % nblk, n0 = 32 * nb;
;                 const int jj = n0 < DFF ? n0 : n0 - DFF; const int drow = (jj >> 7) * 256 + (n0 < DFF ? 0 : 128) + (jj & 127);
;                 transpose_item(a.ffn_w_gu + (size_t)j * DM * 2 * DFF, DM, 2 * DFF, (bf16*)(ws + WS_WGU) + (size_t)j * 2 * DFF * DM, 64 * kb, n0, drow, scr, F.lane); continue; }
;             r -= DEPTH * I_GU;
;             { const int j = r / I_DN; r %= I_DN; const int kb = r / 64, nb = r % 64;
;                 transpose_item(a.ffn_w_down + (size_t)j * DFF * DM, DFF, DM, (bf16*)(ws + WS_WDN) + (size_t)j * DM * DFF, 64 * kb, 32 * nb, 32 * nb, scr, F.lane); }
.Lcv_map1:
	s_mov_b32 s0, 0x5588
	s_cmp_lt_i32 s94, 0x43e0
	s_cselect_b32 s0, 0x3860, s0
	s_cmp_lt_i32 s94, 0x1820
	s_cselect_b32 s0, 0x0, s0
	s_add_i32 s6, s94, s0
	s_branch .Lcv_mapped
.Lcv_map2:
	s_mov_b32 s0, 0xbab8
	s_cmp_lt_i32 s94, 0x4588
	s_cselect_b32 s0, 0x53e0, s0
	s_cmp_lt_i32 s94, 0x2860
	s_cselect_b32 s0, 0x2820, s0
	s_cmp_lt_i32 s94, 0x2820
	s_cselect_b32 s0, 0x2020, s0
	s_cmp_lt_i32 s94, 0x2020
	s_cselect_b32 s0, 0x1820, s0
	s_add_i32 s6, s94, s0
	s_branch .Lcv_mapped

; DI void phase_prologue(const Frame& F0, const Args& a) {
;     ...
;         const int gw = F.vcu * NWAVES + F.wave, NGW = F.G * NWAVES;
;         constexpr int I_IN = 32 * (GIN / 32), I_SQ = 32 * 64, I_GU = 32 * (2 * DFF / 32), I_DN = (DFF / 64) * 64;
;         constexpr int NITEMS = 2 * I_IN + 2 * I_SQ + 2 * I_SQ + DEPTH * I_GU + DEPTH * I_DN;
;         for (int it = gw; it < NITEMS; it += NGW) {
; DI void phase_scan(const Frame& F0, const Args& a, int colmajor) {
;     ...
;     for (int it = F.vcu; it < 256; it += F.G) {
;         if ((it & 31) >= 16) continue;
.Lada_hook_ret:
	s_mov_b32 s98, 0
	v_readlane_b32 s0, v255, 17
	v_readlane_b32 s1, v252, 48
	v_readlane_b32 s44, v252, 49
	v_readlane_b32 s86, v252, 46
	v_readlane_b32 s87, v252, 47
	v_mov_b32_e32 v78, v222
	s_lshr_b32 s4, s1, 5
	s_lshl_b32 s4, s4, 4
	s_and_b32 s5, s1, 15
	s_or_b32 s4, s4, s5
	s_cmp_ge_u32 s44, 8
	s_cbranch_scc1 .Lconv_ret_scan
	s_mul_i32 s4, s4, 8
	s_add_i32 s90, s4, s44
	s_movk_i32 s93, 0x400
	s_mov_b32 s4, 0x7188
	s_mov_b32 s5, 0x9400
	s_cmp_eq_u32 s0, 0
	s_cselect_b32 s92, 2, 3
	s_cselect_b32 s91, s4, s5
	s_cmp_lt_i32 s90, s91
	s_cbranch_scc1 .Lconv_entry
